# hand-scheduled SwiGLU unit epilogue in P1/P9 (f32; folded constants, 20 packed VALU + 16 transcendentals per row group instead of ~57; stepped row addresses)
# baseline (speedup 1.0000x reference)
; #define LAS __attribute__((address_space(3)))
; __device__ __forceinline__ u32x4 pack8(const f32x4 a, const f32x4 b) { u32x4 w; w.x = cvtpk(a[0], a[1]); w.y = cvtpk(a[2], a[3]); w.z = cvtpk(b[0], b[1]); w.w = cvtpk(b[2], b[3]); return w; }
; __device__ __forceinline__ float fast_exp(float x) { return __builtin_amdgcn_exp2f(x * LOG2E); }
; __device__ __forceinline__ float sigmoidf_(float x) { return __builtin_amdgcn_rcpf(1.f + fast_exp(-x)); }
; __device__ __forceinline__ float siluf_(float x) { return x * sigmoidf_(x); }
;     __device__ __forceinline__ void operator()(const Acc& acc, const Unit& u, int wr, int wc, int fr, int fq) const {
;         const int col0 = u.pn * 128 + wc * 32 + 8 * fq;
;         const LAS float* rt = rtab + u.idx * 256 + wr * 64 + fr;
; #pragma unroll
;         for (int ai = 0; ai < 2; ++ai)
; #pragma unroll
;             for (int m = 0; m < 4; ++m) {
;                 const int row = u.pm * BM + ai * HALF + wr * 64 + m * 16 + fr; const float r = rt[ai * HALF + m * 16];
;                 f32x4 h0, h1;
; #pragma unroll
;                 for (int e = 0; e < 4; ++e) { h0[e] = siluf_(acc[ai][0][m][0][e] * r) * (acc[ai][1][m][0][e] * r); h1[e] = siluf_(acc[ai][0][m][1][e] * r) * (acc[ai][1][m][1][e] * r); }
;                 *(u32x4*)(H + (size_t)row * FF + col0) = pack8(h0, h1);
;             }
;     }
.LBB0_587:
	v_lshl_add_u32 v156, s78, 10, v148
	ds_read2_b32 v[158:159], v156 offset1:16
	ds_read2_b32 v[162:163], v156 offset0:32 offset1:48
	ds_read2_b32 v[164:165], v156 offset0:128 offset1:144
	ds_read2_b32 v[166:167], v156 offset0:160 offset1:176
	v_lshl_or_b32 v168, s79, 7, v152
	s_lshl_b32 s19, s30, 8
	v_ashrrev_i32_e32 v169, 31, v168
	s_andn2_b64 vcc, exec, s[0:1]
	v_lshlrev_b64 v[170:171], 1, v[168:169]
	v_mov_b64_e32 v[172:173], s[80:81]
	v_add_u32_e32 v174, s19, v146
	v_mov_b32_e32 v180, 1.0
	v_mad_i64_i32 v[196:197], s[34:35], v174, s74, v[172:173]
	s_mov_b64 s[100:101], 0x16000
	v_lshl_add_u64 v[196:197], v[196:197], 0, v[170:171]
	s_waitcnt lgkmcnt(0)
	v_mul_f32_e32 v176, 0xbfb8aa3b, v158
	v_mul_f32_e32 v178, 0xbf317218, v158
	v_pk_mul_f32 v[126:127], v[126:127], v[176:177] op_sel_hi:[1,0]
	v_pk_mul_f32 v[128:129], v[128:129], v[176:177] op_sel_hi:[1,0]
	v_pk_mul_f32 v[122:123], v[122:123], v[176:177] op_sel_hi:[1,0]
	v_pk_mul_f32 v[124:125], v[124:125], v[176:177] op_sel_hi:[1,0]
	v_exp_f32_e32 v184, v126
	v_exp_f32_e32 v185, v127
	v_exp_f32_e32 v186, v128
	v_exp_f32_e32 v187, v129
	v_exp_f32_e32 v188, v122
	v_exp_f32_e32 v189, v123
	v_exp_f32_e32 v190, v124
	v_exp_f32_e32 v191, v125
	v_pk_mul_f32 v[118:119], v[118:119], v[178:179] op_sel_hi:[1,0]
	v_pk_mul_f32 v[120:121], v[120:121], v[178:179] op_sel_hi:[1,0]
	v_pk_mul_f32 v[114:115], v[114:115], v[178:179] op_sel_hi:[1,0]
	v_pk_mul_f32 v[116:117], v[116:117], v[178:179] op_sel_hi:[1,0]
	v_pk_add_f32 v[184:185], v[184:185], v[180:181] op_sel_hi:[1,0]
	v_pk_add_f32 v[186:187], v[186:187], v[180:181] op_sel_hi:[1,0]
	v_pk_add_f32 v[188:189], v[188:189], v[180:181] op_sel_hi:[1,0]
	v_pk_add_f32 v[190:191], v[190:191], v[180:181] op_sel_hi:[1,0]
	v_rcp_f32_e32 v184, v184
	v_rcp_f32_e32 v185, v185
	v_rcp_f32_e32 v186, v186
	v_rcp_f32_e32 v187, v187
	v_rcp_f32_e32 v188, v188
	v_rcp_f32_e32 v189, v189
	v_rcp_f32_e32 v190, v190
	v_rcp_f32_e32 v191, v191
	v_pk_mul_f32 v[126:127], v[126:127], v[184:185]
	v_pk_mul_f32 v[128:129], v[128:129], v[186:187]
	v_pk_mul_f32 v[122:123], v[122:123], v[188:189]
	v_pk_mul_f32 v[124:125], v[124:125], v[190:191]
	v_pk_mul_f32 v[126:127], v[126:127], v[118:119]
	v_pk_mul_f32 v[128:129], v[128:129], v[120:121]
	v_pk_mul_f32 v[122:123], v[122:123], v[114:115]
	v_pk_mul_f32 v[124:125], v[124:125], v[116:117]
	v_cvt_pk_bf16_f32 v192, v126, v127
	v_cvt_pk_bf16_f32 v193, v128, v129
	v_cvt_pk_bf16_f32 v194, v122, v123
	v_cvt_pk_bf16_f32 v195, v124, v125
	global_store_dwordx4 v[196:197], v[192:195], off
	v_mul_f32_e32 v176, 0xbfb8aa3b, v159
	v_mul_f32_e32 v178, 0xbf317218, v159
	v_lshl_add_u64 v[196:197], v[196:197], 0, s[100:101]
	v_pk_mul_f32 v[110:111], v[110:111], v[176:177] op_sel_hi:[1,0]
	v_pk_mul_f32 v[112:113], v[112:113], v[176:177] op_sel_hi:[1,0]
	v_pk_mul_f32 v[106:107], v[106:107], v[176:177] op_sel_hi:[1,0]
	v_pk_mul_f32 v[108:109], v[108:109], v[176:177] op_sel_hi:[1,0]
	v_exp_f32_e32 v184, v110
	v_exp_f32_e32 v185, v111
	v_exp_f32_e32 v186, v112
	v_exp_f32_e32 v187, v113
	v_exp_f32_e32 v188, v106
	v_exp_f32_e32 v189, v107
	v_exp_f32_e32 v190, v108
	v_exp_f32_e32 v191, v109
	v_pk_mul_f32 v[102:103], v[102:103], v[178:179] op_sel_hi:[1,0]
	v_pk_mul_f32 v[104:105], v[104:105], v[178:179] op_sel_hi:[1,0]
	v_pk_mul_f32 v[98:99], v[98:99], v[178:179] op_sel_hi:[1,0]
	v_pk_mul_f32 v[100:101], v[100:101], v[178:179] op_sel_hi:[1,0]
	v_pk_add_f32 v[184:185], v[184:185], v[180:181] op_sel_hi:[1,0]
	v_pk_add_f32 v[186:187], v[186:187], v[180:181] op_sel_hi:[1,0]
	v_pk_add_f32 v[188:189], v[188:189], v[180:181] op_sel_hi:[1,0]
	v_pk_add_f32 v[190:191], v[190:191], v[180:181] op_sel_hi:[1,0]
	v_rcp_f32_e32 v184, v184
	v_rcp_f32_e32 v185, v185
	v_rcp_f32_e32 v186, v186
	v_rcp_f32_e32 v187, v187
	v_rcp_f32_e32 v188, v188
	v_rcp_f32_e32 v189, v189
	v_rcp_f32_e32 v190, v190
	v_rcp_f32_e32 v191, v191
	v_pk_mul_f32 v[110:111], v[110:111], v[184:185]
	v_pk_mul_f32 v[112:113], v[112:113], v[186:187]
	v_pk_mul_f32 v[106:107], v[106:107], v[188:189]
	v_pk_mul_f32 v[108:109], v[108:109], v[190:191]
	v_pk_mul_f32 v[110:111], v[110:111], v[102:103]
	v_pk_mul_f32 v[112:113], v[112:113], v[104:105]
	v_pk_mul_f32 v[106:107], v[106:107], v[98:99]
	v_pk_mul_f32 v[108:109], v[108:109], v[100:101]
	v_cvt_pk_bf16_f32 v192, v110, v111
	v_cvt_pk_bf16_f32 v193, v112, v113
	v_cvt_pk_bf16_f32 v194, v106, v107
	v_cvt_pk_bf16_f32 v195, v108, v109
	global_store_dwordx4 v[196:197], v[192:195], off
	v_mul_f32_e32 v176, 0xbfb8aa3b, v162
	v_mul_f32_e32 v178, 0xbf317218, v162
	v_lshl_add_u64 v[196:197], v[196:197], 0, s[100:101]
	v_pk_mul_f32 v[94:95], v[94:95], v[176:177] op_sel_hi:[1,0]
	v_pk_mul_f32 v[96:97], v[96:97], v[176:177] op_sel_hi:[1,0]
	v_pk_mul_f32 v[90:91], v[90:91], v[176:177] op_sel_hi:[1,0]
	v_pk_mul_f32 v[92:93], v[92:93], v[176:177] op_sel_hi:[1,0]
	v_exp_f32_e32 v184, v94
	v_exp_f32_e32 v185, v95
	v_exp_f32_e32 v186, v96
	v_exp_f32_e32 v187, v97
	v_exp_f32_e32 v188, v90
	v_exp_f32_e32 v189, v91
	v_exp_f32_e32 v190, v92
	v_exp_f32_e32 v191, v93
	v_pk_mul_f32 v[86:87], v[86:87], v[178:179] op_sel_hi:[1,0]
	v_pk_mul_f32 v[88:89], v[88:89], v[178:179] op_sel_hi:[1,0]
	v_pk_mul_f32 v[82:83], v[82:83], v[178:179] op_sel_hi:[1,0]
	v_pk_mul_f32 v[84:85], v[84:85], v[178:179] op_sel_hi:[1,0]
	v_pk_add_f32 v[184:185], v[184:185], v[180:181] op_sel_hi:[1,0]
	v_pk_add_f32 v[186:187], v[186:187], v[180:181] op_sel_hi:[1,0]
	v_pk_add_f32 v[188:189], v[188:189], v[180:181] op_sel_hi:[1,0]
	v_pk_add_f32 v[190:191], v[190:191], v[180:181] op_sel_hi:[1,0]
	v_rcp_f32_e32 v184, v184
	v_rcp_f32_e32 v185, v185
	v_rcp_f32_e32 v186, v186
	v_rcp_f32_e32 v187, v187
	v_rcp_f32_e32 v188, v188
; __device__ __forceinline__ u32x4 pack8(const f32x4 a, const f32x4 b) { u32x4 w; w.x = cvtpk(a[0], a[1]); w.y = cvtpk(a[2], a[3]); w.z = cvtpk(b[0], b[1]); w.w = cvtpk(b[2], b[3]); return w; }
; __device__ __forceinline__ float fast_exp(float x) { return __builtin_amdgcn_exp2f(x * LOG2E); }
; __device__ __forceinline__ float sigmoidf_(float x) { return __builtin_amdgcn_rcpf(1.f + fast_exp(-x)); }
; __device__ __forceinline__ float siluf_(float x) { return x * sigmoidf_(x); }
;     __device__ __forceinline__ void operator()(const Acc& acc, const Unit& u, int wr, int wc, int fr, int fq) const {
;     ...
;                 const int row = u.pm * BM + ai * HALF + wr * 64 + m * 16 + fr; const float r = rt[ai * HALF + m * 16];
;                 f32x4 h0, h1;
; #pragma unroll
;                 for (int e = 0; e < 4; ++e) { h0[e] = siluf_(acc[ai][0][m][0][e] * r) * (acc[ai][1][m][0][e] * r); h1[e] = siluf_(acc[ai][0][m][1][e] * r) * (acc[ai][1][m][1][e] * r); }
;                 *(u32x4*)(H + (size_t)row * FF + col0) = pack8(h0, h1);
	v_rcp_f32_e32 v189, v189
	v_rcp_f32_e32 v190, v190
	v_rcp_f32_e32 v191, v191
	v_pk_mul_f32 v[94:95], v[94:95], v[184:185]
	v_pk_mul_f32 v[96:97], v[96:97], v[186:187]
	v_pk_mul_f32 v[90:91], v[90:91], v[188:189]
	v_pk_mul_f32 v[92:93], v[92:93], v[190:191]
	v_pk_mul_f32 v[94:95], v[94:95], v[86:87]
	v_pk_mul_f32 v[96:97], v[96:97], v[88:89]
	v_pk_mul_f32 v[90:91], v[90:91], v[82:83]
	v_pk_mul_f32 v[92:93], v[92:93], v[84:85]
	v_cvt_pk_bf16_f32 v192, v94, v95
	v_cvt_pk_bf16_f32 v193, v96, v97
	v_cvt_pk_bf16_f32 v194, v90, v91
	v_cvt_pk_bf16_f32 v195, v92, v93
	global_store_dwordx4 v[196:197], v[192:195], off
	v_mul_f32_e32 v176, 0xbfb8aa3b, v163
	v_mul_f32_e32 v178, 0xbf317218, v163
	v_lshl_add_u64 v[196:197], v[196:197], 0, s[100:101]
	v_pk_mul_f32 v[78:79], v[78:79], v[176:177] op_sel_hi:[1,0]
	v_pk_mul_f32 v[80:81], v[80:81], v[176:177] op_sel_hi:[1,0]
	v_pk_mul_f32 v[74:75], v[74:75], v[176:177] op_sel_hi:[1,0]
	v_pk_mul_f32 v[76:77], v[76:77], v[176:177] op_sel_hi:[1,0]
	v_exp_f32_e32 v184, v78
	v_exp_f32_e32 v185, v79
	v_exp_f32_e32 v186, v80
	v_exp_f32_e32 v187, v81
	v_exp_f32_e32 v188, v74
	v_exp_f32_e32 v189, v75
	v_exp_f32_e32 v190, v76
	v_exp_f32_e32 v191, v77
	v_pk_mul_f32 v[70:71], v[70:71], v[178:179] op_sel_hi:[1,0]
	v_pk_mul_f32 v[72:73], v[72:73], v[178:179] op_sel_hi:[1,0]
	v_pk_mul_f32 v[66:67], v[66:67], v[178:179] op_sel_hi:[1,0]
	v_pk_mul_f32 v[68:69], v[68:69], v[178:179] op_sel_hi:[1,0]
	v_pk_add_f32 v[184:185], v[184:185], v[180:181] op_sel_hi:[1,0]
	v_pk_add_f32 v[186:187], v[186:187], v[180:181] op_sel_hi:[1,0]
	v_pk_add_f32 v[188:189], v[188:189], v[180:181] op_sel_hi:[1,0]
	v_pk_add_f32 v[190:191], v[190:191], v[180:181] op_sel_hi:[1,0]
	v_rcp_f32_e32 v184, v184
	v_rcp_f32_e32 v185, v185
	v_rcp_f32_e32 v186, v186
	v_rcp_f32_e32 v187, v187
	v_rcp_f32_e32 v188, v188
	v_rcp_f32_e32 v189, v189
	v_rcp_f32_e32 v190, v190
	v_rcp_f32_e32 v191, v191
	v_pk_mul_f32 v[78:79], v[78:79], v[184:185]
	v_pk_mul_f32 v[80:81], v[80:81], v[186:187]
	v_pk_mul_f32 v[74:75], v[74:75], v[188:189]
	v_pk_mul_f32 v[76:77], v[76:77], v[190:191]
	v_pk_mul_f32 v[78:79], v[78:79], v[70:71]
	v_pk_mul_f32 v[80:81], v[80:81], v[72:73]
	v_pk_mul_f32 v[74:75], v[74:75], v[66:67]
	v_pk_mul_f32 v[76:77], v[76:77], v[68:69]
	v_cvt_pk_bf16_f32 v192, v78, v79
	v_cvt_pk_bf16_f32 v193, v80, v81
	v_cvt_pk_bf16_f32 v194, v74, v75
	v_cvt_pk_bf16_f32 v195, v76, v77
	global_store_dwordx4 v[196:197], v[192:195], off
	s_mov_b64 s[100:101], 0x6e000
	v_mul_f32_e32 v176, 0xbfb8aa3b, v164
	v_mul_f32_e32 v178, 0xbf317218, v164
	v_lshl_add_u64 v[196:197], v[196:197], 0, s[100:101]
	v_pk_mul_f32 v[62:63], v[62:63], v[176:177] op_sel_hi:[1,0]
	v_pk_mul_f32 v[64:65], v[64:65], v[176:177] op_sel_hi:[1,0]
	v_pk_mul_f32 v[58:59], v[58:59], v[176:177] op_sel_hi:[1,0]
	v_pk_mul_f32 v[60:61], v[60:61], v[176:177] op_sel_hi:[1,0]
	v_exp_f32_e32 v184, v62
	v_exp_f32_e32 v185, v63
	v_exp_f32_e32 v186, v64
	v_exp_f32_e32 v187, v65
	v_exp_f32_e32 v188, v58
	v_exp_f32_e32 v189, v59
	v_exp_f32_e32 v190, v60
	v_exp_f32_e32 v191, v61
	v_pk_mul_f32 v[54:55], v[54:55], v[178:179] op_sel_hi:[1,0]
	v_pk_mul_f32 v[56:57], v[56:57], v[178:179] op_sel_hi:[1,0]
	v_pk_mul_f32 v[50:51], v[50:51], v[178:179] op_sel_hi:[1,0]
	v_pk_mul_f32 v[52:53], v[52:53], v[178:179] op_sel_hi:[1,0]
	v_pk_add_f32 v[184:185], v[184:185], v[180:181] op_sel_hi:[1,0]
	v_pk_add_f32 v[186:187], v[186:187], v[180:181] op_sel_hi:[1,0]
	v_pk_add_f32 v[188:189], v[188:189], v[180:181] op_sel_hi:[1,0]
	v_pk_add_f32 v[190:191], v[190:191], v[180:181] op_sel_hi:[1,0]
	v_rcp_f32_e32 v184, v184
	v_rcp_f32_e32 v185, v185
	v_rcp_f32_e32 v186, v186
	v_rcp_f32_e32 v187, v187
	v_rcp_f32_e32 v188, v188
	v_rcp_f32_e32 v189, v189
	v_rcp_f32_e32 v190, v190
	v_rcp_f32_e32 v191, v191
	v_pk_mul_f32 v[62:63], v[62:63], v[184:185]
	v_pk_mul_f32 v[64:65], v[64:65], v[186:187]
	v_pk_mul_f32 v[58:59], v[58:59], v[188:189]
	v_pk_mul_f32 v[60:61], v[60:61], v[190:191]
	v_pk_mul_f32 v[62:63], v[62:63], v[54:55]
	v_pk_mul_f32 v[64:65], v[64:65], v[56:57]
	v_pk_mul_f32 v[58:59], v[58:59], v[50:51]
	v_pk_mul_f32 v[60:61], v[60:61], v[52:53]
	v_cvt_pk_bf16_f32 v192, v62, v63
	v_cvt_pk_bf16_f32 v193, v64, v65
	v_cvt_pk_bf16_f32 v194, v58, v59
	v_cvt_pk_bf16_f32 v195, v60, v61
	global_store_dwordx4 v[196:197], v[192:195], off
	s_mov_b64 s[100:101], 0x16000
	v_mul_f32_e32 v176, 0xbfb8aa3b, v165
	v_mul_f32_e32 v178, 0xbf317218, v165
	v_lshl_add_u64 v[196:197], v[196:197], 0, s[100:101]
	v_pk_mul_f32 v[46:47], v[46:47], v[176:177] op_sel_hi:[1,0]
	v_pk_mul_f32 v[48:49], v[48:49], v[176:177] op_sel_hi:[1,0]
	v_pk_mul_f32 v[42:43], v[42:43], v[176:177] op_sel_hi:[1,0]
	v_pk_mul_f32 v[44:45], v[44:45], v[176:177] op_sel_hi:[1,0]
	v_exp_f32_e32 v184, v46
	v_exp_f32_e32 v185, v47
	v_exp_f32_e32 v186, v48
	v_exp_f32_e32 v187, v49
	v_exp_f32_e32 v188, v42
	v_exp_f32_e32 v189, v43
	v_exp_f32_e32 v190, v44
	v_exp_f32_e32 v191, v45
	v_pk_mul_f32 v[38:39], v[38:39], v[178:179] op_sel_hi:[1,0]
; __device__ __forceinline__ u32x4 pack8(const f32x4 a, const f32x4 b) { u32x4 w; w.x = cvtpk(a[0], a[1]); w.y = cvtpk(a[2], a[3]); w.z = cvtpk(b[0], b[1]); w.w = cvtpk(b[2], b[3]); return w; }
; __device__ __forceinline__ float fast_exp(float x) { return __builtin_amdgcn_exp2f(x * LOG2E); }
; __device__ __forceinline__ float sigmoidf_(float x) { return __builtin_amdgcn_rcpf(1.f + fast_exp(-x)); }
; __device__ __forceinline__ float siluf_(float x) { return x * sigmoidf_(x); }
;     __device__ __forceinline__ void operator()(const Acc& acc, const Unit& u, int wr, int wc, int fr, int fq) const {
;     ...
;                 const int row = u.pm * BM + ai * HALF + wr * 64 + m * 16 + fr; const float r = rt[ai * HALF + m * 16];
;                 f32x4 h0, h1;
; #pragma unroll
;                 for (int e = 0; e < 4; ++e) { h0[e] = siluf_(acc[ai][0][m][0][e] * r) * (acc[ai][1][m][0][e] * r); h1[e] = siluf_(acc[ai][0][m][1][e] * r) * (acc[ai][1][m][1][e] * r); }
;                 *(u32x4*)(H + (size_t)row * FF + col0) = pack8(h0, h1);
	v_pk_mul_f32 v[40:41], v[40:41], v[178:179] op_sel_hi:[1,0]
	v_pk_mul_f32 v[34:35], v[34:35], v[178:179] op_sel_hi:[1,0]
	v_pk_mul_f32 v[36:37], v[36:37], v[178:179] op_sel_hi:[1,0]
	v_pk_add_f32 v[184:185], v[184:185], v[180:181] op_sel_hi:[1,0]
	v_pk_add_f32 v[186:187], v[186:187], v[180:181] op_sel_hi:[1,0]
	v_pk_add_f32 v[188:189], v[188:189], v[180:181] op_sel_hi:[1,0]
	v_pk_add_f32 v[190:191], v[190:191], v[180:181] op_sel_hi:[1,0]
	v_rcp_f32_e32 v184, v184
	v_rcp_f32_e32 v185, v185
	v_rcp_f32_e32 v186, v186
	v_rcp_f32_e32 v187, v187
	v_rcp_f32_e32 v188, v188
	v_rcp_f32_e32 v189, v189
	v_rcp_f32_e32 v190, v190
	v_rcp_f32_e32 v191, v191
	v_pk_mul_f32 v[46:47], v[46:47], v[184:185]
	v_pk_mul_f32 v[48:49], v[48:49], v[186:187]
	v_pk_mul_f32 v[42:43], v[42:43], v[188:189]
	v_pk_mul_f32 v[44:45], v[44:45], v[190:191]
	v_pk_mul_f32 v[46:47], v[46:47], v[38:39]
	v_pk_mul_f32 v[48:49], v[48:49], v[40:41]
	v_pk_mul_f32 v[42:43], v[42:43], v[34:35]
	v_pk_mul_f32 v[44:45], v[44:45], v[36:37]
	v_cvt_pk_bf16_f32 v192, v46, v47
	v_cvt_pk_bf16_f32 v193, v48, v49
	v_cvt_pk_bf16_f32 v194, v42, v43
	v_cvt_pk_bf16_f32 v195, v44, v45
	global_store_dwordx4 v[196:197], v[192:195], off
	v_mul_f32_e32 v176, 0xbfb8aa3b, v166
	v_mul_f32_e32 v178, 0xbf317218, v166
	v_lshl_add_u64 v[196:197], v[196:197], 0, s[100:101]
	v_pk_mul_f32 v[30:31], v[30:31], v[176:177] op_sel_hi:[1,0]
	v_pk_mul_f32 v[32:33], v[32:33], v[176:177] op_sel_hi:[1,0]
	v_pk_mul_f32 v[26:27], v[26:27], v[176:177] op_sel_hi:[1,0]
	v_pk_mul_f32 v[28:29], v[28:29], v[176:177] op_sel_hi:[1,0]
	v_exp_f32_e32 v184, v30
	v_exp_f32_e32 v185, v31
	v_exp_f32_e32 v186, v32
	v_exp_f32_e32 v187, v33
	v_exp_f32_e32 v188, v26
	v_exp_f32_e32 v189, v27
	v_exp_f32_e32 v190, v28
	v_exp_f32_e32 v191, v29
	v_pk_mul_f32 v[22:23], v[22:23], v[178:179] op_sel_hi:[1,0]
	v_pk_mul_f32 v[24:25], v[24:25], v[178:179] op_sel_hi:[1,0]
	v_pk_mul_f32 v[18:19], v[18:19], v[178:179] op_sel_hi:[1,0]
	v_pk_mul_f32 v[20:21], v[20:21], v[178:179] op_sel_hi:[1,0]
	v_pk_add_f32 v[184:185], v[184:185], v[180:181] op_sel_hi:[1,0]
	v_pk_add_f32 v[186:187], v[186:187], v[180:181] op_sel_hi:[1,0]
	v_pk_add_f32 v[188:189], v[188:189], v[180:181] op_sel_hi:[1,0]
	v_pk_add_f32 v[190:191], v[190:191], v[180:181] op_sel_hi:[1,0]
	v_rcp_f32_e32 v184, v184
	v_rcp_f32_e32 v185, v185
	v_rcp_f32_e32 v186, v186
	v_rcp_f32_e32 v187, v187
	v_rcp_f32_e32 v188, v188
	v_rcp_f32_e32 v189, v189
	v_rcp_f32_e32 v190, v190
	v_rcp_f32_e32 v191, v191
	v_pk_mul_f32 v[30:31], v[30:31], v[184:185]
	v_pk_mul_f32 v[32:33], v[32:33], v[186:187]
	v_pk_mul_f32 v[26:27], v[26:27], v[188:189]
	v_pk_mul_f32 v[28:29], v[28:29], v[190:191]
	v_pk_mul_f32 v[30:31], v[30:31], v[22:23]
	v_pk_mul_f32 v[32:33], v[32:33], v[24:25]
	v_pk_mul_f32 v[26:27], v[26:27], v[18:19]
	v_pk_mul_f32 v[28:29], v[28:29], v[20:21]
	v_cvt_pk_bf16_f32 v192, v30, v31
	v_cvt_pk_bf16_f32 v193, v32, v33
	v_cvt_pk_bf16_f32 v194, v26, v27
	v_cvt_pk_bf16_f32 v195, v28, v29
	global_store_dwordx4 v[196:197], v[192:195], off
	v_mul_f32_e32 v176, 0xbfb8aa3b, v167
	v_mul_f32_e32 v178, 0xbf317218, v167
	v_lshl_add_u64 v[196:197], v[196:197], 0, s[100:101]
	v_pk_mul_f32 v[14:15], v[14:15], v[176:177] op_sel_hi:[1,0]
	v_pk_mul_f32 v[16:17], v[16:17], v[176:177] op_sel_hi:[1,0]
	v_pk_mul_f32 v[10:11], v[10:11], v[176:177] op_sel_hi:[1,0]
	v_pk_mul_f32 v[12:13], v[12:13], v[176:177] op_sel_hi:[1,0]
	v_exp_f32_e32 v184, v14
	v_exp_f32_e32 v185, v15
	v_exp_f32_e32 v186, v16
	v_exp_f32_e32 v187, v17
	v_exp_f32_e32 v188, v10
	v_exp_f32_e32 v189, v11
	v_exp_f32_e32 v190, v12
	v_exp_f32_e32 v191, v13
	v_pk_mul_f32 v[6:7], v[6:7], v[178:179] op_sel_hi:[1,0]
	v_pk_mul_f32 v[8:9], v[8:9], v[178:179] op_sel_hi:[1,0]
	v_pk_mul_f32 v[2:3], v[2:3], v[178:179] op_sel_hi:[1,0]
	v_pk_mul_f32 v[4:5], v[4:5], v[178:179] op_sel_hi:[1,0]
	v_pk_add_f32 v[184:185], v[184:185], v[180:181] op_sel_hi:[1,0]
	v_pk_add_f32 v[186:187], v[186:187], v[180:181] op_sel_hi:[1,0]
	v_pk_add_f32 v[188:189], v[188:189], v[180:181] op_sel_hi:[1,0]
	v_pk_add_f32 v[190:191], v[190:191], v[180:181] op_sel_hi:[1,0]
	v_rcp_f32_e32 v184, v184
	v_rcp_f32_e32 v185, v185
	v_rcp_f32_e32 v186, v186
	v_rcp_f32_e32 v187, v187
	v_rcp_f32_e32 v188, v188
	v_rcp_f32_e32 v189, v189
	v_rcp_f32_e32 v190, v190
	v_rcp_f32_e32 v191, v191
	v_pk_mul_f32 v[14:15], v[14:15], v[184:185]
	v_pk_mul_f32 v[16:17], v[16:17], v[186:187]
	v_pk_mul_f32 v[10:11], v[10:11], v[188:189]
	v_pk_mul_f32 v[12:13], v[12:13], v[190:191]
	v_pk_mul_f32 v[14:15], v[14:15], v[6:7]
	v_pk_mul_f32 v[16:17], v[16:17], v[8:9]
	v_pk_mul_f32 v[10:11], v[10:11], v[2:3]
	v_pk_mul_f32 v[12:13], v[12:13], v[4:5]
	v_cvt_pk_bf16_f32 v192, v14, v15
	v_cvt_pk_bf16_f32 v193, v16, v17
	v_cvt_pk_bf16_f32 v194, v10, v11
	v_cvt_pk_bf16_f32 v195, v12, v13
	s_mov_b64 s[0:1], -1
	global_store_dwordx4 v[196:197], v[192:195], off
	s_cbranch_vccnz .LBB0_576
	s_andn2_b64 vcc, exec, s[4:5]
	s_cbranch_vccnz .LBB0_575
	s_barrier
	s_branch .LBB0_575

; #define LAS __attribute__((address_space(3)))
; __device__ __forceinline__ u32x4 pack8(const f32x4 a, const f32x4 b) { u32x4 w; w.x = cvtpk(a[0], a[1]); w.y = cvtpk(a[2], a[3]); w.z = cvtpk(b[0], b[1]); w.w = cvtpk(b[2], b[3]); return w; }
; __device__ __forceinline__ float fast_exp(float x) { return __builtin_amdgcn_exp2f(x * LOG2E); }
; __device__ __forceinline__ float sigmoidf_(float x) { return __builtin_amdgcn_rcpf(1.f + fast_exp(-x)); }
; __device__ __forceinline__ float siluf_(float x) { return x * sigmoidf_(x); }
;     __device__ __forceinline__ void operator()(const Acc& acc, const Unit& u, int wr, int wc, int fr, int fq) const {
;         const int col0 = u.pn * 128 + wc * 32 + 8 * fq;
;         const LAS float* rt = rtab + u.idx * 256 + wr * 64 + fr;
; #pragma unroll
;         for (int ai = 0; ai < 2; ++ai)
; #pragma unroll
;             for (int m = 0; m < 4; ++m) {
;                 const int row = u.pm * BM + ai * HALF + wr * 64 + m * 16 + fr; const float r = rt[ai * HALF + m * 16];
;                 f32x4 h0, h1;
; #pragma unroll
;                 for (int e = 0; e < 4; ++e) { h0[e] = siluf_(acc[ai][0][m][0][e] * r) * (acc[ai][1][m][0][e] * r); h1[e] = siluf_(acc[ai][0][m][1][e] * r) * (acc[ai][1][m][1][e] * r); }
;                 *(u32x4*)(H + (size_t)row * FF + col0) = pack8(h0, h1);
;             }
;     }
.LBB0_1721:
	v_lshl_add_u32 v156, s43, 10, v148
	ds_read2_b32 v[158:159], v156 offset1:16
	ds_read2_b32 v[162:163], v156 offset0:32 offset1:48
	ds_read2_b32 v[164:165], v156 offset0:128 offset1:144
	ds_read2_b32 v[166:167], v156 offset0:160 offset1:176
	v_lshl_or_b32 v168, s44, 7, v152
	s_lshl_b32 s11, s20, 8
	v_ashrrev_i32_e32 v169, 31, v168
	s_andn2_b64 vcc, exec, s[0:1]
	v_lshlrev_b64 v[170:171], 1, v[168:169]
	v_mov_b64_e32 v[172:173], s[80:81]
	v_add_u32_e32 v174, s11, v146
	v_mov_b32_e32 v180, 1.0
	v_mad_i64_i32 v[196:197], s[22:23], v174, s38, v[172:173]
	s_mov_b64 s[100:101], 0x16000
	v_lshl_add_u64 v[196:197], v[196:197], 0, v[170:171]
	s_waitcnt lgkmcnt(0)
	v_mul_f32_e32 v176, 0xbfb8aa3b, v158
	v_mul_f32_e32 v178, 0xbf317218, v158
	v_pk_mul_f32 v[126:127], v[126:127], v[176:177] op_sel_hi:[1,0]
	v_pk_mul_f32 v[128:129], v[128:129], v[176:177] op_sel_hi:[1,0]
	v_pk_mul_f32 v[122:123], v[122:123], v[176:177] op_sel_hi:[1,0]
	v_pk_mul_f32 v[124:125], v[124:125], v[176:177] op_sel_hi:[1,0]
	v_exp_f32_e32 v184, v126
	v_exp_f32_e32 v185, v127
	v_exp_f32_e32 v186, v128
	v_exp_f32_e32 v187, v129
	v_exp_f32_e32 v188, v122
	v_exp_f32_e32 v189, v123
	v_exp_f32_e32 v190, v124
	v_exp_f32_e32 v191, v125
	v_pk_mul_f32 v[118:119], v[118:119], v[178:179] op_sel_hi:[1,0]
	v_pk_mul_f32 v[120:121], v[120:121], v[178:179] op_sel_hi:[1,0]
	v_pk_mul_f32 v[114:115], v[114:115], v[178:179] op_sel_hi:[1,0]
	v_pk_mul_f32 v[116:117], v[116:117], v[178:179] op_sel_hi:[1,0]
	v_pk_add_f32 v[184:185], v[184:185], v[180:181] op_sel_hi:[1,0]
	v_pk_add_f32 v[186:187], v[186:187], v[180:181] op_sel_hi:[1,0]
	v_pk_add_f32 v[188:189], v[188:189], v[180:181] op_sel_hi:[1,0]
	v_pk_add_f32 v[190:191], v[190:191], v[180:181] op_sel_hi:[1,0]
	v_rcp_f32_e32 v184, v184
	v_rcp_f32_e32 v185, v185
	v_rcp_f32_e32 v186, v186
	v_rcp_f32_e32 v187, v187
	v_rcp_f32_e32 v188, v188
	v_rcp_f32_e32 v189, v189
	v_rcp_f32_e32 v190, v190
	v_rcp_f32_e32 v191, v191
	v_pk_mul_f32 v[126:127], v[126:127], v[184:185]
	v_pk_mul_f32 v[128:129], v[128:129], v[186:187]
	v_pk_mul_f32 v[122:123], v[122:123], v[188:189]
	v_pk_mul_f32 v[124:125], v[124:125], v[190:191]
	v_pk_mul_f32 v[126:127], v[126:127], v[118:119]
	v_pk_mul_f32 v[128:129], v[128:129], v[120:121]
	v_pk_mul_f32 v[122:123], v[122:123], v[114:115]
	v_pk_mul_f32 v[124:125], v[124:125], v[116:117]
	v_cvt_pk_bf16_f32 v192, v126, v127
	v_cvt_pk_bf16_f32 v193, v128, v129
	v_cvt_pk_bf16_f32 v194, v122, v123
	v_cvt_pk_bf16_f32 v195, v124, v125
	global_store_dwordx4 v[196:197], v[192:195], off
	v_mul_f32_e32 v176, 0xbfb8aa3b, v159
	v_mul_f32_e32 v178, 0xbf317218, v159
	v_lshl_add_u64 v[196:197], v[196:197], 0, s[100:101]
	v_pk_mul_f32 v[110:111], v[110:111], v[176:177] op_sel_hi:[1,0]
	v_pk_mul_f32 v[112:113], v[112:113], v[176:177] op_sel_hi:[1,0]
	v_pk_mul_f32 v[106:107], v[106:107], v[176:177] op_sel_hi:[1,0]
	v_pk_mul_f32 v[108:109], v[108:109], v[176:177] op_sel_hi:[1,0]
	v_exp_f32_e32 v184, v110
	v_exp_f32_e32 v185, v111
	v_exp_f32_e32 v186, v112
	v_exp_f32_e32 v187, v113
	v_exp_f32_e32 v188, v106
	v_exp_f32_e32 v189, v107
	v_exp_f32_e32 v190, v108
	v_exp_f32_e32 v191, v109
	v_pk_mul_f32 v[102:103], v[102:103], v[178:179] op_sel_hi:[1,0]
	v_pk_mul_f32 v[104:105], v[104:105], v[178:179] op_sel_hi:[1,0]
	v_pk_mul_f32 v[98:99], v[98:99], v[178:179] op_sel_hi:[1,0]
	v_pk_mul_f32 v[100:101], v[100:101], v[178:179] op_sel_hi:[1,0]
	v_pk_add_f32 v[184:185], v[184:185], v[180:181] op_sel_hi:[1,0]
	v_pk_add_f32 v[186:187], v[186:187], v[180:181] op_sel_hi:[1,0]
	v_pk_add_f32 v[188:189], v[188:189], v[180:181] op_sel_hi:[1,0]
	v_pk_add_f32 v[190:191], v[190:191], v[180:181] op_sel_hi:[1,0]
	v_rcp_f32_e32 v184, v184
	v_rcp_f32_e32 v185, v185
	v_rcp_f32_e32 v186, v186
	v_rcp_f32_e32 v187, v187
	v_rcp_f32_e32 v188, v188
	v_rcp_f32_e32 v189, v189
	v_rcp_f32_e32 v190, v190
	v_rcp_f32_e32 v191, v191
	v_pk_mul_f32 v[110:111], v[110:111], v[184:185]
	v_pk_mul_f32 v[112:113], v[112:113], v[186:187]
	v_pk_mul_f32 v[106:107], v[106:107], v[188:189]
	v_pk_mul_f32 v[108:109], v[108:109], v[190:191]
	v_pk_mul_f32 v[110:111], v[110:111], v[102:103]
	v_pk_mul_f32 v[112:113], v[112:113], v[104:105]
	v_pk_mul_f32 v[106:107], v[106:107], v[98:99]
	v_pk_mul_f32 v[108:109], v[108:109], v[100:101]
	v_cvt_pk_bf16_f32 v192, v110, v111
	v_cvt_pk_bf16_f32 v193, v112, v113
	v_cvt_pk_bf16_f32 v194, v106, v107
	v_cvt_pk_bf16_f32 v195, v108, v109
	global_store_dwordx4 v[196:197], v[192:195], off
	v_mul_f32_e32 v176, 0xbfb8aa3b, v162
	v_mul_f32_e32 v178, 0xbf317218, v162
	v_lshl_add_u64 v[196:197], v[196:197], 0, s[100:101]
	v_pk_mul_f32 v[94:95], v[94:95], v[176:177] op_sel_hi:[1,0]
	v_pk_mul_f32 v[96:97], v[96:97], v[176:177] op_sel_hi:[1,0]
	v_pk_mul_f32 v[90:91], v[90:91], v[176:177] op_sel_hi:[1,0]
	v_pk_mul_f32 v[92:93], v[92:93], v[176:177] op_sel_hi:[1,0]
	v_exp_f32_e32 v184, v94
	v_exp_f32_e32 v185, v95
	v_exp_f32_e32 v186, v96
	v_exp_f32_e32 v187, v97
	v_exp_f32_e32 v188, v90
	v_exp_f32_e32 v189, v91
	v_exp_f32_e32 v190, v92
	v_exp_f32_e32 v191, v93
	v_pk_mul_f32 v[86:87], v[86:87], v[178:179] op_sel_hi:[1,0]
	v_pk_mul_f32 v[88:89], v[88:89], v[178:179] op_sel_hi:[1,0]
	v_pk_mul_f32 v[82:83], v[82:83], v[178:179] op_sel_hi:[1,0]
	v_pk_mul_f32 v[84:85], v[84:85], v[178:179] op_sel_hi:[1,0]
	v_pk_add_f32 v[184:185], v[184:185], v[180:181] op_sel_hi:[1,0]
	v_pk_add_f32 v[186:187], v[186:187], v[180:181] op_sel_hi:[1,0]
	v_pk_add_f32 v[188:189], v[188:189], v[180:181] op_sel_hi:[1,0]
	v_pk_add_f32 v[190:191], v[190:191], v[180:181] op_sel_hi:[1,0]
	v_rcp_f32_e32 v184, v184
	v_rcp_f32_e32 v185, v185
	v_rcp_f32_e32 v186, v186
	v_rcp_f32_e32 v187, v187
	v_rcp_f32_e32 v188, v188
; __device__ __forceinline__ u32x4 pack8(const f32x4 a, const f32x4 b) { u32x4 w; w.x = cvtpk(a[0], a[1]); w.y = cvtpk(a[2], a[3]); w.z = cvtpk(b[0], b[1]); w.w = cvtpk(b[2], b[3]); return w; }
; __device__ __forceinline__ float fast_exp(float x) { return __builtin_amdgcn_exp2f(x * LOG2E); }
; __device__ __forceinline__ float sigmoidf_(float x) { return __builtin_amdgcn_rcpf(1.f + fast_exp(-x)); }
; __device__ __forceinline__ float siluf_(float x) { return x * sigmoidf_(x); }
;     __device__ __forceinline__ void operator()(const Acc& acc, const Unit& u, int wr, int wc, int fr, int fq) const {
;     ...
;                 const int row = u.pm * BM + ai * HALF + wr * 64 + m * 16 + fr; const float r = rt[ai * HALF + m * 16];
;                 f32x4 h0, h1;
; #pragma unroll
;                 for (int e = 0; e < 4; ++e) { h0[e] = siluf_(acc[ai][0][m][0][e] * r) * (acc[ai][1][m][0][e] * r); h1[e] = siluf_(acc[ai][0][m][1][e] * r) * (acc[ai][1][m][1][e] * r); }
;                 *(u32x4*)(H + (size_t)row * FF + col0) = pack8(h0, h1);
	v_rcp_f32_e32 v189, v189
	v_rcp_f32_e32 v190, v190
	v_rcp_f32_e32 v191, v191
	v_pk_mul_f32 v[94:95], v[94:95], v[184:185]
	v_pk_mul_f32 v[96:97], v[96:97], v[186:187]
	v_pk_mul_f32 v[90:91], v[90:91], v[188:189]
	v_pk_mul_f32 v[92:93], v[92:93], v[190:191]
	v_pk_mul_f32 v[94:95], v[94:95], v[86:87]
	v_pk_mul_f32 v[96:97], v[96:97], v[88:89]
	v_pk_mul_f32 v[90:91], v[90:91], v[82:83]
	v_pk_mul_f32 v[92:93], v[92:93], v[84:85]
	v_cvt_pk_bf16_f32 v192, v94, v95
	v_cvt_pk_bf16_f32 v193, v96, v97
	v_cvt_pk_bf16_f32 v194, v90, v91
	v_cvt_pk_bf16_f32 v195, v92, v93
	global_store_dwordx4 v[196:197], v[192:195], off
	v_mul_f32_e32 v176, 0xbfb8aa3b, v163
	v_mul_f32_e32 v178, 0xbf317218, v163
	v_lshl_add_u64 v[196:197], v[196:197], 0, s[100:101]
	v_pk_mul_f32 v[78:79], v[78:79], v[176:177] op_sel_hi:[1,0]
	v_pk_mul_f32 v[80:81], v[80:81], v[176:177] op_sel_hi:[1,0]
	v_pk_mul_f32 v[74:75], v[74:75], v[176:177] op_sel_hi:[1,0]
	v_pk_mul_f32 v[76:77], v[76:77], v[176:177] op_sel_hi:[1,0]
	v_exp_f32_e32 v184, v78
	v_exp_f32_e32 v185, v79
	v_exp_f32_e32 v186, v80
	v_exp_f32_e32 v187, v81
	v_exp_f32_e32 v188, v74
	v_exp_f32_e32 v189, v75
	v_exp_f32_e32 v190, v76
	v_exp_f32_e32 v191, v77
	v_pk_mul_f32 v[70:71], v[70:71], v[178:179] op_sel_hi:[1,0]
	v_pk_mul_f32 v[72:73], v[72:73], v[178:179] op_sel_hi:[1,0]
	v_pk_mul_f32 v[66:67], v[66:67], v[178:179] op_sel_hi:[1,0]
	v_pk_mul_f32 v[68:69], v[68:69], v[178:179] op_sel_hi:[1,0]
	v_pk_add_f32 v[184:185], v[184:185], v[180:181] op_sel_hi:[1,0]
	v_pk_add_f32 v[186:187], v[186:187], v[180:181] op_sel_hi:[1,0]
	v_pk_add_f32 v[188:189], v[188:189], v[180:181] op_sel_hi:[1,0]
	v_pk_add_f32 v[190:191], v[190:191], v[180:181] op_sel_hi:[1,0]
	v_rcp_f32_e32 v184, v184
	v_rcp_f32_e32 v185, v185
	v_rcp_f32_e32 v186, v186
	v_rcp_f32_e32 v187, v187
	v_rcp_f32_e32 v188, v188
	v_rcp_f32_e32 v189, v189
	v_rcp_f32_e32 v190, v190
	v_rcp_f32_e32 v191, v191
	v_pk_mul_f32 v[78:79], v[78:79], v[184:185]
	v_pk_mul_f32 v[80:81], v[80:81], v[186:187]
	v_pk_mul_f32 v[74:75], v[74:75], v[188:189]
	v_pk_mul_f32 v[76:77], v[76:77], v[190:191]
	v_pk_mul_f32 v[78:79], v[78:79], v[70:71]
	v_pk_mul_f32 v[80:81], v[80:81], v[72:73]
	v_pk_mul_f32 v[74:75], v[74:75], v[66:67]
	v_pk_mul_f32 v[76:77], v[76:77], v[68:69]
	v_cvt_pk_bf16_f32 v192, v78, v79
	v_cvt_pk_bf16_f32 v193, v80, v81
	v_cvt_pk_bf16_f32 v194, v74, v75
	v_cvt_pk_bf16_f32 v195, v76, v77
	global_store_dwordx4 v[196:197], v[192:195], off
	s_mov_b64 s[100:101], 0x6e000
	v_mul_f32_e32 v176, 0xbfb8aa3b, v164
	v_mul_f32_e32 v178, 0xbf317218, v164
	v_lshl_add_u64 v[196:197], v[196:197], 0, s[100:101]
	v_pk_mul_f32 v[62:63], v[62:63], v[176:177] op_sel_hi:[1,0]
	v_pk_mul_f32 v[64:65], v[64:65], v[176:177] op_sel_hi:[1,0]
	v_pk_mul_f32 v[58:59], v[58:59], v[176:177] op_sel_hi:[1,0]
	v_pk_mul_f32 v[60:61], v[60:61], v[176:177] op_sel_hi:[1,0]
	v_exp_f32_e32 v184, v62
	v_exp_f32_e32 v185, v63
	v_exp_f32_e32 v186, v64
	v_exp_f32_e32 v187, v65
	v_exp_f32_e32 v188, v58
	v_exp_f32_e32 v189, v59
	v_exp_f32_e32 v190, v60
	v_exp_f32_e32 v191, v61
	v_pk_mul_f32 v[54:55], v[54:55], v[178:179] op_sel_hi:[1,0]
	v_pk_mul_f32 v[56:57], v[56:57], v[178:179] op_sel_hi:[1,0]
	v_pk_mul_f32 v[50:51], v[50:51], v[178:179] op_sel_hi:[1,0]
	v_pk_mul_f32 v[52:53], v[52:53], v[178:179] op_sel_hi:[1,0]
	v_pk_add_f32 v[184:185], v[184:185], v[180:181] op_sel_hi:[1,0]
	v_pk_add_f32 v[186:187], v[186:187], v[180:181] op_sel_hi:[1,0]
	v_pk_add_f32 v[188:189], v[188:189], v[180:181] op_sel_hi:[1,0]
	v_pk_add_f32 v[190:191], v[190:191], v[180:181] op_sel_hi:[1,0]
	v_rcp_f32_e32 v184, v184
	v_rcp_f32_e32 v185, v185
	v_rcp_f32_e32 v186, v186
	v_rcp_f32_e32 v187, v187
	v_rcp_f32_e32 v188, v188
	v_rcp_f32_e32 v189, v189
	v_rcp_f32_e32 v190, v190
	v_rcp_f32_e32 v191, v191
	v_pk_mul_f32 v[62:63], v[62:63], v[184:185]
	v_pk_mul_f32 v[64:65], v[64:65], v[186:187]
	v_pk_mul_f32 v[58:59], v[58:59], v[188:189]
	v_pk_mul_f32 v[60:61], v[60:61], v[190:191]
	v_pk_mul_f32 v[62:63], v[62:63], v[54:55]
	v_pk_mul_f32 v[64:65], v[64:65], v[56:57]
	v_pk_mul_f32 v[58:59], v[58:59], v[50:51]
	v_pk_mul_f32 v[60:61], v[60:61], v[52:53]
	v_cvt_pk_bf16_f32 v192, v62, v63
	v_cvt_pk_bf16_f32 v193, v64, v65
	v_cvt_pk_bf16_f32 v194, v58, v59
	v_cvt_pk_bf16_f32 v195, v60, v61
	global_store_dwordx4 v[196:197], v[192:195], off
	s_mov_b64 s[100:101], 0x16000
	v_mul_f32_e32 v176, 0xbfb8aa3b, v165
	v_mul_f32_e32 v178, 0xbf317218, v165
	v_lshl_add_u64 v[196:197], v[196:197], 0, s[100:101]
	v_pk_mul_f32 v[46:47], v[46:47], v[176:177] op_sel_hi:[1,0]
	v_pk_mul_f32 v[48:49], v[48:49], v[176:177] op_sel_hi:[1,0]
	v_pk_mul_f32 v[42:43], v[42:43], v[176:177] op_sel_hi:[1,0]
	v_pk_mul_f32 v[44:45], v[44:45], v[176:177] op_sel_hi:[1,0]
	v_exp_f32_e32 v184, v46
	v_exp_f32_e32 v185, v47
	v_exp_f32_e32 v186, v48
	v_exp_f32_e32 v187, v49
	v_exp_f32_e32 v188, v42
	v_exp_f32_e32 v189, v43
	v_exp_f32_e32 v190, v44
	v_exp_f32_e32 v191, v45
	v_pk_mul_f32 v[38:39], v[38:39], v[178:179] op_sel_hi:[1,0]
; __device__ __forceinline__ u32x4 pack8(const f32x4 a, const f32x4 b) { u32x4 w; w.x = cvtpk(a[0], a[1]); w.y = cvtpk(a[2], a[3]); w.z = cvtpk(b[0], b[1]); w.w = cvtpk(b[2], b[3]); return w; }
; __device__ __forceinline__ float fast_exp(float x) { return __builtin_amdgcn_exp2f(x * LOG2E); }
; __device__ __forceinline__ float sigmoidf_(float x) { return __builtin_amdgcn_rcpf(1.f + fast_exp(-x)); }
; __device__ __forceinline__ float siluf_(float x) { return x * sigmoidf_(x); }
;     __device__ __forceinline__ void operator()(const Acc& acc, const Unit& u, int wr, int wc, int fr, int fq) const {
;     ...
;                 const int row = u.pm * BM + ai * HALF + wr * 64 + m * 16 + fr; const float r = rt[ai * HALF + m * 16];
;                 f32x4 h0, h1;
; #pragma unroll
;                 for (int e = 0; e < 4; ++e) { h0[e] = siluf_(acc[ai][0][m][0][e] * r) * (acc[ai][1][m][0][e] * r); h1[e] = siluf_(acc[ai][0][m][1][e] * r) * (acc[ai][1][m][1][e] * r); }
;                 *(u32x4*)(H + (size_t)row * FF + col0) = pack8(h0, h1);
	v_pk_mul_f32 v[40:41], v[40:41], v[178:179] op_sel_hi:[1,0]
	v_pk_mul_f32 v[34:35], v[34:35], v[178:179] op_sel_hi:[1,0]
	v_pk_mul_f32 v[36:37], v[36:37], v[178:179] op_sel_hi:[1,0]
	v_pk_add_f32 v[184:185], v[184:185], v[180:181] op_sel_hi:[1,0]
	v_pk_add_f32 v[186:187], v[186:187], v[180:181] op_sel_hi:[1,0]
	v_pk_add_f32 v[188:189], v[188:189], v[180:181] op_sel_hi:[1,0]
	v_pk_add_f32 v[190:191], v[190:191], v[180:181] op_sel_hi:[1,0]
	v_rcp_f32_e32 v184, v184
	v_rcp_f32_e32 v185, v185
	v_rcp_f32_e32 v186, v186
	v_rcp_f32_e32 v187, v187
	v_rcp_f32_e32 v188, v188
	v_rcp_f32_e32 v189, v189
	v_rcp_f32_e32 v190, v190
	v_rcp_f32_e32 v191, v191
	v_pk_mul_f32 v[46:47], v[46:47], v[184:185]
	v_pk_mul_f32 v[48:49], v[48:49], v[186:187]
	v_pk_mul_f32 v[42:43], v[42:43], v[188:189]
	v_pk_mul_f32 v[44:45], v[44:45], v[190:191]
	v_pk_mul_f32 v[46:47], v[46:47], v[38:39]
	v_pk_mul_f32 v[48:49], v[48:49], v[40:41]
	v_pk_mul_f32 v[42:43], v[42:43], v[34:35]
	v_pk_mul_f32 v[44:45], v[44:45], v[36:37]
	v_cvt_pk_bf16_f32 v192, v46, v47
	v_cvt_pk_bf16_f32 v193, v48, v49
	v_cvt_pk_bf16_f32 v194, v42, v43
	v_cvt_pk_bf16_f32 v195, v44, v45
	global_store_dwordx4 v[196:197], v[192:195], off
	v_mul_f32_e32 v176, 0xbfb8aa3b, v166
	v_mul_f32_e32 v178, 0xbf317218, v166
	v_lshl_add_u64 v[196:197], v[196:197], 0, s[100:101]
	v_pk_mul_f32 v[30:31], v[30:31], v[176:177] op_sel_hi:[1,0]
	v_pk_mul_f32 v[32:33], v[32:33], v[176:177] op_sel_hi:[1,0]
	v_pk_mul_f32 v[26:27], v[26:27], v[176:177] op_sel_hi:[1,0]
	v_pk_mul_f32 v[28:29], v[28:29], v[176:177] op_sel_hi:[1,0]
	v_exp_f32_e32 v184, v30
	v_exp_f32_e32 v185, v31
	v_exp_f32_e32 v186, v32
	v_exp_f32_e32 v187, v33
	v_exp_f32_e32 v188, v26
	v_exp_f32_e32 v189, v27
	v_exp_f32_e32 v190, v28
	v_exp_f32_e32 v191, v29
	v_pk_mul_f32 v[22:23], v[22:23], v[178:179] op_sel_hi:[1,0]
	v_pk_mul_f32 v[24:25], v[24:25], v[178:179] op_sel_hi:[1,0]
	v_pk_mul_f32 v[18:19], v[18:19], v[178:179] op_sel_hi:[1,0]
	v_pk_mul_f32 v[20:21], v[20:21], v[178:179] op_sel_hi:[1,0]
	v_pk_add_f32 v[184:185], v[184:185], v[180:181] op_sel_hi:[1,0]
	v_pk_add_f32 v[186:187], v[186:187], v[180:181] op_sel_hi:[1,0]
	v_pk_add_f32 v[188:189], v[188:189], v[180:181] op_sel_hi:[1,0]
	v_pk_add_f32 v[190:191], v[190:191], v[180:181] op_sel_hi:[1,0]
	v_rcp_f32_e32 v184, v184
	v_rcp_f32_e32 v185, v185
	v_rcp_f32_e32 v186, v186
	v_rcp_f32_e32 v187, v187
	v_rcp_f32_e32 v188, v188
	v_rcp_f32_e32 v189, v189
	v_rcp_f32_e32 v190, v190
	v_rcp_f32_e32 v191, v191
	v_pk_mul_f32 v[30:31], v[30:31], v[184:185]
	v_pk_mul_f32 v[32:33], v[32:33], v[186:187]
	v_pk_mul_f32 v[26:27], v[26:27], v[188:189]
	v_pk_mul_f32 v[28:29], v[28:29], v[190:191]
	v_pk_mul_f32 v[30:31], v[30:31], v[22:23]
	v_pk_mul_f32 v[32:33], v[32:33], v[24:25]
	v_pk_mul_f32 v[26:27], v[26:27], v[18:19]
	v_pk_mul_f32 v[28:29], v[28:29], v[20:21]
	v_cvt_pk_bf16_f32 v192, v30, v31
	v_cvt_pk_bf16_f32 v193, v32, v33
	v_cvt_pk_bf16_f32 v194, v26, v27
	v_cvt_pk_bf16_f32 v195, v28, v29
	global_store_dwordx4 v[196:197], v[192:195], off
	v_mul_f32_e32 v176, 0xbfb8aa3b, v167
	v_mul_f32_e32 v178, 0xbf317218, v167
	v_lshl_add_u64 v[196:197], v[196:197], 0, s[100:101]
	v_pk_mul_f32 v[14:15], v[14:15], v[176:177] op_sel_hi:[1,0]
	v_pk_mul_f32 v[16:17], v[16:17], v[176:177] op_sel_hi:[1,0]
	v_pk_mul_f32 v[10:11], v[10:11], v[176:177] op_sel_hi:[1,0]
	v_pk_mul_f32 v[12:13], v[12:13], v[176:177] op_sel_hi:[1,0]
	v_exp_f32_e32 v184, v14
	v_exp_f32_e32 v185, v15
	v_exp_f32_e32 v186, v16
	v_exp_f32_e32 v187, v17
	v_exp_f32_e32 v188, v10
	v_exp_f32_e32 v189, v11
	v_exp_f32_e32 v190, v12
	v_exp_f32_e32 v191, v13
	v_pk_mul_f32 v[6:7], v[6:7], v[178:179] op_sel_hi:[1,0]
	v_pk_mul_f32 v[8:9], v[8:9], v[178:179] op_sel_hi:[1,0]
	v_pk_mul_f32 v[2:3], v[2:3], v[178:179] op_sel_hi:[1,0]
	v_pk_mul_f32 v[4:5], v[4:5], v[178:179] op_sel_hi:[1,0]
	v_pk_add_f32 v[184:185], v[184:185], v[180:181] op_sel_hi:[1,0]
	v_pk_add_f32 v[186:187], v[186:187], v[180:181] op_sel_hi:[1,0]
	v_pk_add_f32 v[188:189], v[188:189], v[180:181] op_sel_hi:[1,0]
	v_pk_add_f32 v[190:191], v[190:191], v[180:181] op_sel_hi:[1,0]
	v_rcp_f32_e32 v184, v184
	v_rcp_f32_e32 v185, v185
	v_rcp_f32_e32 v186, v186
	v_rcp_f32_e32 v187, v187
	v_rcp_f32_e32 v188, v188
	v_rcp_f32_e32 v189, v189
	v_rcp_f32_e32 v190, v190
	v_rcp_f32_e32 v191, v191
	v_pk_mul_f32 v[14:15], v[14:15], v[184:185]
	v_pk_mul_f32 v[16:17], v[16:17], v[186:187]
	v_pk_mul_f32 v[10:11], v[10:11], v[188:189]
	v_pk_mul_f32 v[12:13], v[12:13], v[190:191]
	v_pk_mul_f32 v[14:15], v[14:15], v[6:7]
	v_pk_mul_f32 v[16:17], v[16:17], v[8:9]
	v_pk_mul_f32 v[10:11], v[10:11], v[2:3]
	v_pk_mul_f32 v[12:13], v[12:13], v[4:5]
	v_cvt_pk_bf16_f32 v192, v14, v15
	v_cvt_pk_bf16_f32 v193, v16, v17
	v_cvt_pk_bf16_f32 v194, v10, v11
	v_cvt_pk_bf16_f32 v195, v12, v13
	s_mov_b64 s[0:1], -1
	global_store_dwordx4 v[196:197], v[192:195], off
	s_cbranch_vccnz .LBB0_1710
	s_andn2_b64 vcc, exec, s[4:5]
	s_cbranch_vccnz .LBB0_1709
	s_barrier
	s_branch .LBB0_1709
